# R1_0: the four f32 input rows of each wave are requested right after the workgroup arrives at barrier 5, before polling it, so the HBM latency overlaps the barrier wait
# baseline (speedup 1.0000x reference)
.LBB0_512:
	s_waitcnt vmcnt(0)
	s_waitcnt vmcnt(0) lgkmcnt(0)
	s_barrier
	v_readlane_b32 s98, v219, 30
	s_nop 1
	s_and_b32 s99, s98, 31
	s_lshl_b32 s99, s99, 3
	s_lshr_b32 s98, s98, 5
	s_or_b32 s98, s99, s98
	s_lshl_b32 s98, s98, 5
	v_readfirstlane_b32 s99, v166
	s_nop 1
	s_add_i32 s98, s98, s99
	s_cmp_gt_u32 s98, 0xfff
	s_cselect_b32 s100, s38, s36
	s_cselect_b32 s101, s39, s37
	s_and_b32 s98, s98, 0xfff
	s_lshl_b32 s98, s98, 12
	s_add_u32 s100, s100, s98
	s_addc_u32 s101, s101, 0
	v_and_b32_e32 v221, 0x1f8, v144
	v_lshlrev_b32_e32 v221, 2, v221
	global_load_dwordx4 v[186:189], v221, s[100:101] nt
	global_load_dwordx4 v[190:193], v221, s[100:101] offset:16 nt
	global_load_dwordx4 v[194:197], v221, s[100:101] offset:2048 nt
	global_load_dwordx4 v[198:201], v221, s[100:101] offset:2064 nt
	s_add_u32 s100, s100, 0x1000
	s_addc_u32 s101, s101, 0
	global_load_dwordx4 v[224:227], v221, s[100:101] nt
	global_load_dwordx4 v[228:231], v221, s[100:101] offset:16 nt
	global_load_dwordx4 v[232:235], v221, s[100:101] offset:2048 nt
	global_load_dwordx4 v[236:239], v221, s[100:101] offset:2064 nt
	s_add_u32 s100, s100, 0x1000
	s_addc_u32 s101, s101, 0
	global_load_dwordx4 v[240:243], v221, s[100:101] nt
	global_load_dwordx4 v[244:247], v221, s[100:101] offset:16 nt
	global_load_dwordx4 v[248:251], v221, s[100:101] offset:2048 nt
	global_load_dwordx4 v[252:255], v221, s[100:101] offset:2064 nt
	s_add_u32 s100, s100, 0x1000
	s_addc_u32 s101, s101, 0
	global_load_dwordx4 v[202:205], v221, s[100:101] nt
	global_load_dwordx4 v[206:209], v221, s[100:101] offset:16 nt
	global_load_dwordx4 v[210:213], v221, s[100:101] offset:2048 nt
	global_load_dwordx4 v[150:153], v221, s[100:101] offset:2064 nt
	s_mov_b64 s[4:5], exec
	v_readlane_b32 s0, v219, 25
	v_readlane_b32 s1, v219, 26
	s_and_b64 s[0:1], s[4:5], s[0:1]
	s_mov_b64 exec, s[0:1]
	s_cbranch_execz .LBB0_564
	v_readlane_b32 s0, v219, 27
	v_readlane_b32 s1, v219, 28
	v_readlane_b32 s2, v219, 30
	s_waitcnt lgkmcnt(0)
	buffer_inv sc1
	s_and_b32 s3, s2, 31
	s_lshl_b32 s3, s3, 7
	s_add_i32 s3, s3, 64
	v_mov_b32_e32 v1, s3
	v_mov_b32_e32 v0, 1
	s_nop 1
	global_atomic_add v1, v0, s[0:1]
	s_mov_b32 s15, 0
